# RWKV scan consumer chunk hand-scheduled: 16 steps unrolled, register double-buffered operand prefetch, state-update re-associated off the reduction chain, no hazard nops
# speedup vs baseline: 1.0450x; 1.0238x over previous
; DI void scan_item(const __attribute__((address_space(4))) Args& a, LAS unsigned char* lds, int ws_, bool is_prompt, int seq, int h, int half, bool dry = false) {
;     ...
;     auto consume = [&](int bsel) {
;         const LAS unsigned char* B = lds + bsel * SC_BUF;
;         const LAS float* opb = (const LAS float*)B + c0;
;         const LAS float* vvb = (const LAS float*)(B + SC_OPS) + i0;
;         const LAS float* scb = (const LAS float*)(B + SC_OPS + SC_VV);
;         LAS float* ybb = cg8 == 0 ? (LAS float*)(B + SC_OPS + SC_VV + SC_SC) + (i0 & 31) : (LAS float*)(lds + 2 * SC_BUF) + (tid & 255);
;         f32x4 n[10]; float nv; f32x2 nbk;
;     ...
;         SC_LOAD(0)
; #pragma unroll 4
;         for (int t = 0; t < SC_CH; ++t) {
;             f32x4 c[10];
; #pragma unroll
;             for (int q = 0; q < 10; ++q) c[q] = n[q];
;             const float v0 = nv; const f32x2 bk = nbk;
;             SC_LOAD(t + 1)
;             __builtin_amdgcn_sched_barrier(0);
;             f32x2 aA = sp[0] * c[0].xy, aY = sp[0] * c[2].xy;
;             aA = sp[1] * c[0].zw + aA; aY = sp[1] * c[2].zw + aY;
;             aA = sp[2] * c[1].xy + aA; aY = sp[2] * c[3].xy + aY;
;             aA = sp[3] * c[1].zw + aA; aY = sp[3] * c[3].zw + aY;
;             float da = aA.x + aA.y, dy = aY.x + aY.y;
;             asm("s_nop 1\n\t"
;                 "v_add_f32_dpp %0, %0, %0 quad_perm:[1,0,3,2] row_mask:0xf bank_mask:0xf bound_ctrl:1\n\t"
;                 "v_add_f32_dpp %1, %1, %1 quad_perm:[1,0,3,2] row_mask:0xf bank_mask:0xf bound_ctrl:1\n\t"
;                 "s_nop 0\n\t"
;                 "v_add_f32_dpp %0, %0, %0 quad_perm:[2,3,0,1] row_mask:0xf bank_mask:0xf bound_ctrl:1\n\t"
;                 "v_add_f32_dpp %1, %1, %1 quad_perm:[2,3,0,1] row_mask:0xf bank_mask:0xf bound_ctrl:1\n\t"
;                 "s_nop 0\n\t"
;                 "v_add_f32_dpp %0, %0, %0 row_half_mirror row_mask:0xf bank_mask:0xf bound_ctrl:1\n\t"
;                 "v_add_f32_dpp %1, %1, %1 row_half_mirror row_mask:0xf bank_mask:0xf bound_ctrl:1"
;                 : "+v"(da), "+v"(dy));
;             {
;                 f32x2 t0;
;                 t0 = c[8].xy * v0; t0 = c[6].xy * da + t0; sp[0] = sp[0] * c[4].xy + t0;
;                 t0 = c[8].zw * v0; t0 = c[6].zw * da + t0; sp[1] = sp[1] * c[4].zw + t0;
;                 t0 = c[9].xy * v0; t0 = c[7].xy * da + t0; sp[2] = sp[2] * c[5].xy + t0;
.LBB0_1535:
	s_and_b64 vcc, exec, s[74:75]
	s_cbranch_vccz .LBB0_1523
	s_bitcmp1_b32 s24, 0
	s_cselect_b32 s34, 0x6900, 0
	s_add_i32 s35, s34, 0
	s_waitcnt vmcnt(0)
	v_lshl_add_u32 v120, v110, 2, s35
	v_lshl_add_u32 v96, v111, 2, s35
	v_lshl_add_u32 v136, v115, 2, s35
	v_mov_b32_e32 v121, s35
	v_add_u32_e32 v136, 0x6100, v136
	v_cndmask_b32_e64 v95, v116, v136, s[8:9]
	ds_read_b128 v[40:43], v120
	ds_read_b128 v[44:47], v120 offset:16
	ds_read_b128 v[48:51], v120 offset:256
	ds_read_b128 v[52:55], v120 offset:272
	ds_read_b128 v[56:59], v120 offset:512
	ds_read_b128 v[60:63], v120 offset:528
	ds_read_b128 v[64:67], v120 offset:768
	ds_read_b128 v[68:71], v120 offset:784
	ds_read_b128 v[72:75], v120 offset:1024
	ds_read_b128 v[76:79], v120 offset:1040
	ds_read_b32 v94, v96 offset:20480
	ds_read_b64 v[108:109], v121 offset:24576
	ds_read_b128 v[190:193], v120 offset:1280
	ds_read_b128 v[194:197], v120 offset:1296
	ds_read_b128 v[198:201], v120 offset:1536
	ds_read_b128 v[202:205], v120 offset:1552
	ds_read_b128 v[206:209], v120 offset:1792
	ds_read_b128 v[210:213], v120 offset:1808
	ds_read_b128 v[214:217], v120 offset:2048
	ds_read_b128 v[218:221], v120 offset:2064
	ds_read_b128 v[222:225], v120 offset:2304
	ds_read_b128 v[226:229], v120 offset:2320
	ds_read_b32 v230, v96 offset:20736
	ds_read_b64 v[232:233], v121 offset:24592
	s_waitcnt lgkmcnt(12)
	v_pk_mul_f32 v[122:123], v[38:39], v[42:43]
	v_pk_mul_f32 v[124:125], v[38:39], v[50:51]
	v_pk_fma_f32 v[122:123], v[36:37], v[40:41], v[122:123]
	v_pk_fma_f32 v[124:125], v[36:37], v[48:49], v[124:125]
	v_pk_fma_f32 v[122:123], v[32:33], v[44:45], v[122:123]
	v_pk_fma_f32 v[124:125], v[32:33], v[52:53], v[124:125]
	v_pk_fma_f32 v[122:123], v[34:35], v[46:47], v[122:123]
	v_pk_fma_f32 v[124:125], v[34:35], v[54:55], v[124:125]
	v_pk_mul_f32 v[126:127], v[72:73], v[94:95] op_sel_hi:[1,0]
	v_add_f32_e32 v166, v122, v123
	v_add_f32_e32 v168, v124, v125
	v_pk_mul_f32 v[128:129], v[74:75], v[94:95] op_sel_hi:[1,0]
	v_pk_mul_f32 v[130:131], v[76:77], v[94:95] op_sel_hi:[1,0]
	v_add_f32_dpp v166, v166, v166 quad_perm:[1,0,3,2] row_mask:0xf bank_mask:0xf bound_ctrl:1
	v_add_f32_dpp v168, v168, v168 quad_perm:[1,0,3,2] row_mask:0xf bank_mask:0xf bound_ctrl:1
	v_pk_mul_f32 v[132:133], v[78:79], v[94:95] op_sel_hi:[1,0]
	v_pk_fma_f32 v[126:127], v[36:37], v[56:57], v[126:127]
	v_add_f32_dpp v166, v166, v166 quad_perm:[2,3,0,1] row_mask:0xf bank_mask:0xf bound_ctrl:1
	v_add_f32_dpp v168, v168, v168 quad_perm:[2,3,0,1] row_mask:0xf bank_mask:0xf bound_ctrl:1
	v_pk_fma_f32 v[128:129], v[38:39], v[58:59], v[128:129]
	v_pk_fma_f32 v[130:131], v[32:33], v[60:61], v[130:131]
	v_add_f32_dpp v166, v166, v166 row_half_mirror row_mask:0xf bank_mask:0xf bound_ctrl:1
	v_add_f32_dpp v168, v168, v168 row_half_mirror row_mask:0xf bank_mask:0xf bound_ctrl:1
	v_pk_fma_f32 v[132:133], v[34:35], v[62:63], v[132:133]
	v_mov_b32_e32 v167, v94
	v_pk_fma_f32 v[36:37], v[64:65], v[166:167], v[126:127] op_sel_hi:[1,0,1]
	v_pk_fma_f32 v[38:39], v[66:67], v[166:167], v[128:129] op_sel_hi:[1,0,1]
	v_pk_fma_f32 v[32:33], v[68:69], v[166:167], v[130:131] op_sel_hi:[1,0,1]
	v_pk_fma_f32 v[34:35], v[70:71], v[166:167], v[132:133] op_sel_hi:[1,0,1]
	v_pk_mul_f32 v[134:135], v[166:167], v[108:109]
	s_nop 0
	v_add_f32_e32 v136, v168, v134
	v_add_f32_e32 v136, v135, v136
	ds_write_b32 v95, v136
	ds_read_b128 v[40:43], v120 offset:2560
	ds_read_b128 v[44:47], v120 offset:2576
	ds_read_b128 v[48:51], v120 offset:2816
	ds_read_b128 v[52:55], v120 offset:2832
	ds_read_b128 v[56:59], v120 offset:3072
	ds_read_b128 v[60:63], v120 offset:3088
	ds_read_b128 v[64:67], v120 offset:3328
	ds_read_b128 v[68:71], v120 offset:3344
	ds_read_b128 v[72:75], v120 offset:3584
	ds_read_b128 v[76:79], v120 offset:3600
	ds_read_b32 v94, v96 offset:20992
	ds_read_b64 v[108:109], v121 offset:24608
	s_waitcnt lgkmcnt(12)
	v_pk_mul_f32 v[122:123], v[38:39], v[192:193]
	v_pk_mul_f32 v[124:125], v[38:39], v[200:201]
	v_pk_fma_f32 v[122:123], v[36:37], v[190:191], v[122:123]
	v_pk_fma_f32 v[124:125], v[36:37], v[198:199], v[124:125]
	v_pk_fma_f32 v[122:123], v[32:33], v[194:195], v[122:123]
	v_pk_fma_f32 v[124:125], v[32:33], v[202:203], v[124:125]
	v_pk_fma_f32 v[122:123], v[34:35], v[196:197], v[122:123]
	v_pk_fma_f32 v[124:125], v[34:35], v[204:205], v[124:125]
	v_pk_mul_f32 v[126:127], v[222:223], v[230:231] op_sel_hi:[1,0]
	v_add_f32_e32 v166, v122, v123
	v_add_f32_e32 v168, v124, v125
	v_pk_mul_f32 v[128:129], v[224:225], v[230:231] op_sel_hi:[1,0]
	v_pk_mul_f32 v[130:131], v[226:227], v[230:231] op_sel_hi:[1,0]
	v_add_f32_dpp v166, v166, v166 quad_perm:[1,0,3,2] row_mask:0xf bank_mask:0xf bound_ctrl:1
	v_add_f32_dpp v168, v168, v168 quad_perm:[1,0,3,2] row_mask:0xf bank_mask:0xf bound_ctrl:1
	v_pk_mul_f32 v[132:133], v[228:229], v[230:231] op_sel_hi:[1,0]
	v_pk_fma_f32 v[126:127], v[36:37], v[206:207], v[126:127]
	v_add_f32_dpp v166, v166, v166 quad_perm:[2,3,0,1] row_mask:0xf bank_mask:0xf bound_ctrl:1
	v_add_f32_dpp v168, v168, v168 quad_perm:[2,3,0,1] row_mask:0xf bank_mask:0xf bound_ctrl:1
	v_pk_fma_f32 v[128:129], v[38:39], v[208:209], v[128:129]
	v_pk_fma_f32 v[130:131], v[32:33], v[210:211], v[130:131]
	v_add_f32_dpp v166, v166, v166 row_half_mirror row_mask:0xf bank_mask:0xf bound_ctrl:1
	v_add_f32_dpp v168, v168, v168 row_half_mirror row_mask:0xf bank_mask:0xf bound_ctrl:1
	v_pk_fma_f32 v[132:133], v[34:35], v[212:213], v[132:133]
	v_mov_b32_e32 v167, v230
	v_pk_fma_f32 v[36:37], v[214:215], v[166:167], v[126:127] op_sel_hi:[1,0,1]
	v_pk_fma_f32 v[38:39], v[216:217], v[166:167], v[128:129] op_sel_hi:[1,0,1]
	v_pk_fma_f32 v[32:33], v[218:219], v[166:167], v[130:131] op_sel_hi:[1,0,1]
	v_pk_fma_f32 v[34:35], v[220:221], v[166:167], v[132:133] op_sel_hi:[1,0,1]
	v_pk_mul_f32 v[134:135], v[166:167], v[232:233]
	s_nop 0
	v_add_f32_e32 v136, v168, v134
	v_add_f32_e32 v136, v135, v136
	ds_write_b32 v95, v136 offset:128
	ds_read_b128 v[190:193], v120 offset:3840
	ds_read_b128 v[194:197], v120 offset:3856
	ds_read_b128 v[198:201], v120 offset:4096
	ds_read_b128 v[202:205], v120 offset:4112
	ds_read_b128 v[206:209], v120 offset:4352
	ds_read_b128 v[210:213], v120 offset:4368
	ds_read_b128 v[214:217], v120 offset:4608
	ds_read_b128 v[218:221], v120 offset:4624
	ds_read_b128 v[222:225], v120 offset:4864
	ds_read_b128 v[226:229], v120 offset:4880
	ds_read_b32 v230, v96 offset:21248
	ds_read_b64 v[232:233], v121 offset:24624
	s_waitcnt lgkmcnt(12)
; #define SC_LOAD(t) { _Pragma("unroll") for (int q = 0; q < 5; ++q) { n[2 * q] = *(const LAS f32x4*)(opb + (t) * 320 + q * 64); n[2 * q + 1] = *(const LAS f32x4*)(opb + (t) * 320 + q * 64 + 4); } \
;                      nv = vvb[(t) * 64]; nbk = *(const LAS f32x2*)(scb + (t) * 4); }
; DI void scan_item(const __attribute__((address_space(4))) Args& a, LAS unsigned char* lds, int ws_, bool is_prompt, int seq, int h, int half, bool dry = false) {
;     ...
; #pragma unroll 4
;         for (int t = 0; t < SC_CH; ++t) {
;             f32x4 c[10];
; #pragma unroll
;             for (int q = 0; q < 10; ++q) c[q] = n[q];
;             const float v0 = nv; const f32x2 bk = nbk;
;             SC_LOAD(t + 1)
;             __builtin_amdgcn_sched_barrier(0);
;             f32x2 aA = sp[0] * c[0].xy, aY = sp[0] * c[2].xy;
;             aA = sp[1] * c[0].zw + aA; aY = sp[1] * c[2].zw + aY;
;             aA = sp[2] * c[1].xy + aA; aY = sp[2] * c[3].xy + aY;
;             aA = sp[3] * c[1].zw + aA; aY = sp[3] * c[3].zw + aY;
;             float da = aA.x + aA.y, dy = aY.x + aY.y;
;             asm("s_nop 1\n\t"
;                 "v_add_f32_dpp %0, %0, %0 quad_perm:[1,0,3,2] row_mask:0xf bank_mask:0xf bound_ctrl:1\n\t"
;                 "v_add_f32_dpp %1, %1, %1 quad_perm:[1,0,3,2] row_mask:0xf bank_mask:0xf bound_ctrl:1\n\t"
;                 "s_nop 0\n\t"
;                 "v_add_f32_dpp %0, %0, %0 quad_perm:[2,3,0,1] row_mask:0xf bank_mask:0xf bound_ctrl:1\n\t"
;                 "v_add_f32_dpp %1, %1, %1 quad_perm:[2,3,0,1] row_mask:0xf bank_mask:0xf bound_ctrl:1\n\t"
;                 "s_nop 0\n\t"
;                 "v_add_f32_dpp %0, %0, %0 row_half_mirror row_mask:0xf bank_mask:0xf bound_ctrl:1\n\t"
;                 "v_add_f32_dpp %1, %1, %1 row_half_mirror row_mask:0xf bank_mask:0xf bound_ctrl:1"
;                 : "+v"(da), "+v"(dy));
;             {
;                 f32x2 t0;
;                 t0 = c[8].xy * v0; t0 = c[6].xy * da + t0; sp[0] = sp[0] * c[4].xy + t0;
;                 t0 = c[8].zw * v0; t0 = c[6].zw * da + t0; sp[1] = sp[1] * c[4].zw + t0;
;                 t0 = c[9].xy * v0; t0 = c[7].xy * da + t0; sp[2] = sp[2] * c[5].xy + t0;
;                 t0 = c[9].zw * v0; t0 = c[7].zw * da + t0; sp[3] = sp[3] * c[5].zw + t0;
;             }
;             ybb[t * 32] = dy + da * bk.x + v0 * bk.y;
	v_pk_mul_f32 v[122:123], v[38:39], v[42:43]
	v_pk_mul_f32 v[124:125], v[38:39], v[50:51]
	v_pk_fma_f32 v[122:123], v[36:37], v[40:41], v[122:123]
	v_pk_fma_f32 v[124:125], v[36:37], v[48:49], v[124:125]
	v_pk_fma_f32 v[122:123], v[32:33], v[44:45], v[122:123]
	v_pk_fma_f32 v[124:125], v[32:33], v[52:53], v[124:125]
	v_pk_fma_f32 v[122:123], v[34:35], v[46:47], v[122:123]
	v_pk_fma_f32 v[124:125], v[34:35], v[54:55], v[124:125]
	v_pk_mul_f32 v[126:127], v[72:73], v[94:95] op_sel_hi:[1,0]
	v_add_f32_e32 v166, v122, v123
	v_add_f32_e32 v168, v124, v125
	v_pk_mul_f32 v[128:129], v[74:75], v[94:95] op_sel_hi:[1,0]
	v_pk_mul_f32 v[130:131], v[76:77], v[94:95] op_sel_hi:[1,0]
	v_add_f32_dpp v166, v166, v166 quad_perm:[1,0,3,2] row_mask:0xf bank_mask:0xf bound_ctrl:1
	v_add_f32_dpp v168, v168, v168 quad_perm:[1,0,3,2] row_mask:0xf bank_mask:0xf bound_ctrl:1
	v_pk_mul_f32 v[132:133], v[78:79], v[94:95] op_sel_hi:[1,0]
	v_pk_fma_f32 v[126:127], v[36:37], v[56:57], v[126:127]
	v_add_f32_dpp v166, v166, v166 quad_perm:[2,3,0,1] row_mask:0xf bank_mask:0xf bound_ctrl:1
	v_add_f32_dpp v168, v168, v168 quad_perm:[2,3,0,1] row_mask:0xf bank_mask:0xf bound_ctrl:1
	v_pk_fma_f32 v[128:129], v[38:39], v[58:59], v[128:129]
	v_pk_fma_f32 v[130:131], v[32:33], v[60:61], v[130:131]
	v_add_f32_dpp v166, v166, v166 row_half_mirror row_mask:0xf bank_mask:0xf bound_ctrl:1
	v_add_f32_dpp v168, v168, v168 row_half_mirror row_mask:0xf bank_mask:0xf bound_ctrl:1
	v_pk_fma_f32 v[132:133], v[34:35], v[62:63], v[132:133]
	v_mov_b32_e32 v167, v94
	v_pk_fma_f32 v[36:37], v[64:65], v[166:167], v[126:127] op_sel_hi:[1,0,1]
	v_pk_fma_f32 v[38:39], v[66:67], v[166:167], v[128:129] op_sel_hi:[1,0,1]
	v_pk_fma_f32 v[32:33], v[68:69], v[166:167], v[130:131] op_sel_hi:[1,0,1]
	v_pk_fma_f32 v[34:35], v[70:71], v[166:167], v[132:133] op_sel_hi:[1,0,1]
	v_pk_mul_f32 v[134:135], v[166:167], v[108:109]
	s_nop 0
	v_add_f32_e32 v136, v168, v134
	v_add_f32_e32 v136, v135, v136
	ds_write_b32 v95, v136 offset:256
	ds_read_b128 v[40:43], v120 offset:5120
	ds_read_b128 v[44:47], v120 offset:5136
	ds_read_b128 v[48:51], v120 offset:5376
	ds_read_b128 v[52:55], v120 offset:5392
	ds_read_b128 v[56:59], v120 offset:5632
	ds_read_b128 v[60:63], v120 offset:5648
	ds_read_b128 v[64:67], v120 offset:5888
	ds_read_b128 v[68:71], v120 offset:5904
	ds_read_b128 v[72:75], v120 offset:6144
	ds_read_b128 v[76:79], v120 offset:6160
	ds_read_b32 v94, v96 offset:21504
	ds_read_b64 v[108:109], v121 offset:24640
	s_waitcnt lgkmcnt(12)
	v_pk_mul_f32 v[122:123], v[38:39], v[192:193]
	v_pk_mul_f32 v[124:125], v[38:39], v[200:201]
	v_pk_fma_f32 v[122:123], v[36:37], v[190:191], v[122:123]
	v_pk_fma_f32 v[124:125], v[36:37], v[198:199], v[124:125]
	v_pk_fma_f32 v[122:123], v[32:33], v[194:195], v[122:123]
	v_pk_fma_f32 v[124:125], v[32:33], v[202:203], v[124:125]
	v_pk_fma_f32 v[122:123], v[34:35], v[196:197], v[122:123]
	v_pk_fma_f32 v[124:125], v[34:35], v[204:205], v[124:125]
	v_pk_mul_f32 v[126:127], v[222:223], v[230:231] op_sel_hi:[1,0]
	v_add_f32_e32 v166, v122, v123
	v_add_f32_e32 v168, v124, v125
	v_pk_mul_f32 v[128:129], v[224:225], v[230:231] op_sel_hi:[1,0]
	v_pk_mul_f32 v[130:131], v[226:227], v[230:231] op_sel_hi:[1,0]
	v_add_f32_dpp v166, v166, v166 quad_perm:[1,0,3,2] row_mask:0xf bank_mask:0xf bound_ctrl:1
	v_add_f32_dpp v168, v168, v168 quad_perm:[1,0,3,2] row_mask:0xf bank_mask:0xf bound_ctrl:1
	v_pk_mul_f32 v[132:133], v[228:229], v[230:231] op_sel_hi:[1,0]
	v_pk_fma_f32 v[126:127], v[36:37], v[206:207], v[126:127]
	v_add_f32_dpp v166, v166, v166 quad_perm:[2,3,0,1] row_mask:0xf bank_mask:0xf bound_ctrl:1
	v_add_f32_dpp v168, v168, v168 quad_perm:[2,3,0,1] row_mask:0xf bank_mask:0xf bound_ctrl:1
	v_pk_fma_f32 v[128:129], v[38:39], v[208:209], v[128:129]
	v_pk_fma_f32 v[130:131], v[32:33], v[210:211], v[130:131]
	v_add_f32_dpp v166, v166, v166 row_half_mirror row_mask:0xf bank_mask:0xf bound_ctrl:1
	v_add_f32_dpp v168, v168, v168 row_half_mirror row_mask:0xf bank_mask:0xf bound_ctrl:1
	v_pk_fma_f32 v[132:133], v[34:35], v[212:213], v[132:133]
	v_mov_b32_e32 v167, v230
	v_pk_fma_f32 v[36:37], v[214:215], v[166:167], v[126:127] op_sel_hi:[1,0,1]
	v_pk_fma_f32 v[38:39], v[216:217], v[166:167], v[128:129] op_sel_hi:[1,0,1]
	v_pk_fma_f32 v[32:33], v[218:219], v[166:167], v[130:131] op_sel_hi:[1,0,1]
	v_pk_fma_f32 v[34:35], v[220:221], v[166:167], v[132:133] op_sel_hi:[1,0,1]
	v_pk_mul_f32 v[134:135], v[166:167], v[232:233]
	s_nop 0
	v_add_f32_e32 v136, v168, v134
	v_add_f32_e32 v136, v135, v136
	ds_write_b32 v95, v136 offset:384
	ds_read_b128 v[190:193], v120 offset:6400
	ds_read_b128 v[194:197], v120 offset:6416
	ds_read_b128 v[198:201], v120 offset:6656
	ds_read_b128 v[202:205], v120 offset:6672
	ds_read_b128 v[206:209], v120 offset:6912
	ds_read_b128 v[210:213], v120 offset:6928
	ds_read_b128 v[214:217], v120 offset:7168
	ds_read_b128 v[218:221], v120 offset:7184
	ds_read_b128 v[222:225], v120 offset:7424
	ds_read_b128 v[226:229], v120 offset:7440
	ds_read_b32 v230, v96 offset:21760
	ds_read_b64 v[232:233], v121 offset:24656
	s_waitcnt lgkmcnt(12)
; #define SC_LOAD(t) { _Pragma("unroll") for (int q = 0; q < 5; ++q) { n[2 * q] = *(const LAS f32x4*)(opb + (t) * 320 + q * 64); n[2 * q + 1] = *(const LAS f32x4*)(opb + (t) * 320 + q * 64 + 4); } \
;                      nv = vvb[(t) * 64]; nbk = *(const LAS f32x2*)(scb + (t) * 4); }
; DI void scan_item(const __attribute__((address_space(4))) Args& a, LAS unsigned char* lds, int ws_, bool is_prompt, int seq, int h, int half, bool dry = false) {
;     ...
; #pragma unroll 4
;         for (int t = 0; t < SC_CH; ++t) {
;             f32x4 c[10];
; #pragma unroll
;             for (int q = 0; q < 10; ++q) c[q] = n[q];
;             const float v0 = nv; const f32x2 bk = nbk;
;             SC_LOAD(t + 1)
;             __builtin_amdgcn_sched_barrier(0);
;             f32x2 aA = sp[0] * c[0].xy, aY = sp[0] * c[2].xy;
;             aA = sp[1] * c[0].zw + aA; aY = sp[1] * c[2].zw + aY;
;             aA = sp[2] * c[1].xy + aA; aY = sp[2] * c[3].xy + aY;
;             aA = sp[3] * c[1].zw + aA; aY = sp[3] * c[3].zw + aY;
;             float da = aA.x + aA.y, dy = aY.x + aY.y;
;             asm("s_nop 1\n\t"
;                 "v_add_f32_dpp %0, %0, %0 quad_perm:[1,0,3,2] row_mask:0xf bank_mask:0xf bound_ctrl:1\n\t"
;                 "v_add_f32_dpp %1, %1, %1 quad_perm:[1,0,3,2] row_mask:0xf bank_mask:0xf bound_ctrl:1\n\t"
;                 "s_nop 0\n\t"
;                 "v_add_f32_dpp %0, %0, %0 quad_perm:[2,3,0,1] row_mask:0xf bank_mask:0xf bound_ctrl:1\n\t"
;                 "v_add_f32_dpp %1, %1, %1 quad_perm:[2,3,0,1] row_mask:0xf bank_mask:0xf bound_ctrl:1\n\t"
;                 "s_nop 0\n\t"
;                 "v_add_f32_dpp %0, %0, %0 row_half_mirror row_mask:0xf bank_mask:0xf bound_ctrl:1\n\t"
;                 "v_add_f32_dpp %1, %1, %1 row_half_mirror row_mask:0xf bank_mask:0xf bound_ctrl:1"
;                 : "+v"(da), "+v"(dy));
;             {
;                 f32x2 t0;
;                 t0 = c[8].xy * v0; t0 = c[6].xy * da + t0; sp[0] = sp[0] * c[4].xy + t0;
;                 t0 = c[8].zw * v0; t0 = c[6].zw * da + t0; sp[1] = sp[1] * c[4].zw + t0;
;                 t0 = c[9].xy * v0; t0 = c[7].xy * da + t0; sp[2] = sp[2] * c[5].xy + t0;
;                 t0 = c[9].zw * v0; t0 = c[7].zw * da + t0; sp[3] = sp[3] * c[5].zw + t0;
;             }
;             ybb[t * 32] = dy + da * bk.x + v0 * bk.y;
	v_pk_mul_f32 v[122:123], v[38:39], v[42:43]
	v_pk_mul_f32 v[124:125], v[38:39], v[50:51]
	v_pk_fma_f32 v[122:123], v[36:37], v[40:41], v[122:123]
	v_pk_fma_f32 v[124:125], v[36:37], v[48:49], v[124:125]
	v_pk_fma_f32 v[122:123], v[32:33], v[44:45], v[122:123]
	v_pk_fma_f32 v[124:125], v[32:33], v[52:53], v[124:125]
	v_pk_fma_f32 v[122:123], v[34:35], v[46:47], v[122:123]
	v_pk_fma_f32 v[124:125], v[34:35], v[54:55], v[124:125]
	v_pk_mul_f32 v[126:127], v[72:73], v[94:95] op_sel_hi:[1,0]
	v_add_f32_e32 v166, v122, v123
	v_add_f32_e32 v168, v124, v125
	v_pk_mul_f32 v[128:129], v[74:75], v[94:95] op_sel_hi:[1,0]
	v_pk_mul_f32 v[130:131], v[76:77], v[94:95] op_sel_hi:[1,0]
	v_add_f32_dpp v166, v166, v166 quad_perm:[1,0,3,2] row_mask:0xf bank_mask:0xf bound_ctrl:1
	v_add_f32_dpp v168, v168, v168 quad_perm:[1,0,3,2] row_mask:0xf bank_mask:0xf bound_ctrl:1
	v_pk_mul_f32 v[132:133], v[78:79], v[94:95] op_sel_hi:[1,0]
	v_pk_fma_f32 v[126:127], v[36:37], v[56:57], v[126:127]
	v_add_f32_dpp v166, v166, v166 quad_perm:[2,3,0,1] row_mask:0xf bank_mask:0xf bound_ctrl:1
	v_add_f32_dpp v168, v168, v168 quad_perm:[2,3,0,1] row_mask:0xf bank_mask:0xf bound_ctrl:1
	v_pk_fma_f32 v[128:129], v[38:39], v[58:59], v[128:129]
	v_pk_fma_f32 v[130:131], v[32:33], v[60:61], v[130:131]
	v_add_f32_dpp v166, v166, v166 row_half_mirror row_mask:0xf bank_mask:0xf bound_ctrl:1
	v_add_f32_dpp v168, v168, v168 row_half_mirror row_mask:0xf bank_mask:0xf bound_ctrl:1
	v_pk_fma_f32 v[132:133], v[34:35], v[62:63], v[132:133]
	v_mov_b32_e32 v167, v94
	v_pk_fma_f32 v[36:37], v[64:65], v[166:167], v[126:127] op_sel_hi:[1,0,1]
	v_pk_fma_f32 v[38:39], v[66:67], v[166:167], v[128:129] op_sel_hi:[1,0,1]
	v_pk_fma_f32 v[32:33], v[68:69], v[166:167], v[130:131] op_sel_hi:[1,0,1]
	v_pk_fma_f32 v[34:35], v[70:71], v[166:167], v[132:133] op_sel_hi:[1,0,1]
	v_pk_mul_f32 v[134:135], v[166:167], v[108:109]
	s_nop 0
	v_add_f32_e32 v136, v168, v134
	v_add_f32_e32 v136, v135, v136
	ds_write_b32 v95, v136 offset:512
	ds_read_b128 v[40:43], v120 offset:7680
	ds_read_b128 v[44:47], v120 offset:7696
	ds_read_b128 v[48:51], v120 offset:7936
	ds_read_b128 v[52:55], v120 offset:7952
	ds_read_b128 v[56:59], v120 offset:8192
	ds_read_b128 v[60:63], v120 offset:8208
	ds_read_b128 v[64:67], v120 offset:8448
	ds_read_b128 v[68:71], v120 offset:8464
	ds_read_b128 v[72:75], v120 offset:8704
	ds_read_b128 v[76:79], v120 offset:8720
	ds_read_b32 v94, v96 offset:22016
	ds_read_b64 v[108:109], v121 offset:24672
	s_waitcnt lgkmcnt(12)
	v_pk_mul_f32 v[122:123], v[38:39], v[192:193]
	v_pk_mul_f32 v[124:125], v[38:39], v[200:201]
	v_pk_fma_f32 v[122:123], v[36:37], v[190:191], v[122:123]
	v_pk_fma_f32 v[124:125], v[36:37], v[198:199], v[124:125]
	v_pk_fma_f32 v[122:123], v[32:33], v[194:195], v[122:123]
	v_pk_fma_f32 v[124:125], v[32:33], v[202:203], v[124:125]
	v_pk_fma_f32 v[122:123], v[34:35], v[196:197], v[122:123]
	v_pk_fma_f32 v[124:125], v[34:35], v[204:205], v[124:125]
	v_pk_mul_f32 v[126:127], v[222:223], v[230:231] op_sel_hi:[1,0]
	v_add_f32_e32 v166, v122, v123
	v_add_f32_e32 v168, v124, v125
	v_pk_mul_f32 v[128:129], v[224:225], v[230:231] op_sel_hi:[1,0]
	v_pk_mul_f32 v[130:131], v[226:227], v[230:231] op_sel_hi:[1,0]
	v_add_f32_dpp v166, v166, v166 quad_perm:[1,0,3,2] row_mask:0xf bank_mask:0xf bound_ctrl:1
	v_add_f32_dpp v168, v168, v168 quad_perm:[1,0,3,2] row_mask:0xf bank_mask:0xf bound_ctrl:1
	v_pk_mul_f32 v[132:133], v[228:229], v[230:231] op_sel_hi:[1,0]
	v_pk_fma_f32 v[126:127], v[36:37], v[206:207], v[126:127]
	v_add_f32_dpp v166, v166, v166 quad_perm:[2,3,0,1] row_mask:0xf bank_mask:0xf bound_ctrl:1
	v_add_f32_dpp v168, v168, v168 quad_perm:[2,3,0,1] row_mask:0xf bank_mask:0xf bound_ctrl:1
	v_pk_fma_f32 v[128:129], v[38:39], v[208:209], v[128:129]
	v_pk_fma_f32 v[130:131], v[32:33], v[210:211], v[130:131]
	v_add_f32_dpp v166, v166, v166 row_half_mirror row_mask:0xf bank_mask:0xf bound_ctrl:1
	v_add_f32_dpp v168, v168, v168 row_half_mirror row_mask:0xf bank_mask:0xf bound_ctrl:1
	v_pk_fma_f32 v[132:133], v[34:35], v[212:213], v[132:133]
	v_mov_b32_e32 v167, v230
	v_pk_fma_f32 v[36:37], v[214:215], v[166:167], v[126:127] op_sel_hi:[1,0,1]
	v_pk_fma_f32 v[38:39], v[216:217], v[166:167], v[128:129] op_sel_hi:[1,0,1]
	v_pk_fma_f32 v[32:33], v[218:219], v[166:167], v[130:131] op_sel_hi:[1,0,1]
	v_pk_fma_f32 v[34:35], v[220:221], v[166:167], v[132:133] op_sel_hi:[1,0,1]
	v_pk_mul_f32 v[134:135], v[166:167], v[232:233]
	s_nop 0
	v_add_f32_e32 v136, v168, v134
	v_add_f32_e32 v136, v135, v136
	ds_write_b32 v95, v136 offset:640
	ds_read_b128 v[190:193], v120 offset:8960
	ds_read_b128 v[194:197], v120 offset:8976
	ds_read_b128 v[198:201], v120 offset:9216
	ds_read_b128 v[202:205], v120 offset:9232
	ds_read_b128 v[206:209], v120 offset:9472
	ds_read_b128 v[210:213], v120 offset:9488
	ds_read_b128 v[214:217], v120 offset:9728
	ds_read_b128 v[218:221], v120 offset:9744
	ds_read_b128 v[222:225], v120 offset:9984
	ds_read_b128 v[226:229], v120 offset:10000
	ds_read_b32 v230, v96 offset:22272
	ds_read_b64 v[232:233], v121 offset:24688
	s_waitcnt lgkmcnt(12)
; #define SC_LOAD(t) { _Pragma("unroll") for (int q = 0; q < 5; ++q) { n[2 * q] = *(const LAS f32x4*)(opb + (t) * 320 + q * 64); n[2 * q + 1] = *(const LAS f32x4*)(opb + (t) * 320 + q * 64 + 4); } \
;                      nv = vvb[(t) * 64]; nbk = *(const LAS f32x2*)(scb + (t) * 4); }
; DI void scan_item(const __attribute__((address_space(4))) Args& a, LAS unsigned char* lds, int ws_, bool is_prompt, int seq, int h, int half, bool dry = false) {
;     ...
; #pragma unroll 4
;         for (int t = 0; t < SC_CH; ++t) {
;             f32x4 c[10];
; #pragma unroll
;             for (int q = 0; q < 10; ++q) c[q] = n[q];
;             const float v0 = nv; const f32x2 bk = nbk;
;             SC_LOAD(t + 1)
;             __builtin_amdgcn_sched_barrier(0);
;             f32x2 aA = sp[0] * c[0].xy, aY = sp[0] * c[2].xy;
;             aA = sp[1] * c[0].zw + aA; aY = sp[1] * c[2].zw + aY;
;             aA = sp[2] * c[1].xy + aA; aY = sp[2] * c[3].xy + aY;
;             aA = sp[3] * c[1].zw + aA; aY = sp[3] * c[3].zw + aY;
;             float da = aA.x + aA.y, dy = aY.x + aY.y;
;             asm("s_nop 1\n\t"
;                 "v_add_f32_dpp %0, %0, %0 quad_perm:[1,0,3,2] row_mask:0xf bank_mask:0xf bound_ctrl:1\n\t"
;                 "v_add_f32_dpp %1, %1, %1 quad_perm:[1,0,3,2] row_mask:0xf bank_mask:0xf bound_ctrl:1\n\t"
;                 "s_nop 0\n\t"
;                 "v_add_f32_dpp %0, %0, %0 quad_perm:[2,3,0,1] row_mask:0xf bank_mask:0xf bound_ctrl:1\n\t"
;                 "v_add_f32_dpp %1, %1, %1 quad_perm:[2,3,0,1] row_mask:0xf bank_mask:0xf bound_ctrl:1\n\t"
;                 "s_nop 0\n\t"
;                 "v_add_f32_dpp %0, %0, %0 row_half_mirror row_mask:0xf bank_mask:0xf bound_ctrl:1\n\t"
;                 "v_add_f32_dpp %1, %1, %1 row_half_mirror row_mask:0xf bank_mask:0xf bound_ctrl:1"
;                 : "+v"(da), "+v"(dy));
;             {
;                 f32x2 t0;
;                 t0 = c[8].xy * v0; t0 = c[6].xy * da + t0; sp[0] = sp[0] * c[4].xy + t0;
;                 t0 = c[8].zw * v0; t0 = c[6].zw * da + t0; sp[1] = sp[1] * c[4].zw + t0;
;                 t0 = c[9].xy * v0; t0 = c[7].xy * da + t0; sp[2] = sp[2] * c[5].xy + t0;
;                 t0 = c[9].zw * v0; t0 = c[7].zw * da + t0; sp[3] = sp[3] * c[5].zw + t0;
;             }
;             ybb[t * 32] = dy + da * bk.x + v0 * bk.y;
	v_pk_mul_f32 v[122:123], v[38:39], v[42:43]
	v_pk_mul_f32 v[124:125], v[38:39], v[50:51]
	v_pk_fma_f32 v[122:123], v[36:37], v[40:41], v[122:123]
	v_pk_fma_f32 v[124:125], v[36:37], v[48:49], v[124:125]
	v_pk_fma_f32 v[122:123], v[32:33], v[44:45], v[122:123]
	v_pk_fma_f32 v[124:125], v[32:33], v[52:53], v[124:125]
	v_pk_fma_f32 v[122:123], v[34:35], v[46:47], v[122:123]
	v_pk_fma_f32 v[124:125], v[34:35], v[54:55], v[124:125]
	v_pk_mul_f32 v[126:127], v[72:73], v[94:95] op_sel_hi:[1,0]
	v_add_f32_e32 v166, v122, v123
	v_add_f32_e32 v168, v124, v125
	v_pk_mul_f32 v[128:129], v[74:75], v[94:95] op_sel_hi:[1,0]
	v_pk_mul_f32 v[130:131], v[76:77], v[94:95] op_sel_hi:[1,0]
	v_add_f32_dpp v166, v166, v166 quad_perm:[1,0,3,2] row_mask:0xf bank_mask:0xf bound_ctrl:1
	v_add_f32_dpp v168, v168, v168 quad_perm:[1,0,3,2] row_mask:0xf bank_mask:0xf bound_ctrl:1
	v_pk_mul_f32 v[132:133], v[78:79], v[94:95] op_sel_hi:[1,0]
	v_pk_fma_f32 v[126:127], v[36:37], v[56:57], v[126:127]
	v_add_f32_dpp v166, v166, v166 quad_perm:[2,3,0,1] row_mask:0xf bank_mask:0xf bound_ctrl:1
	v_add_f32_dpp v168, v168, v168 quad_perm:[2,3,0,1] row_mask:0xf bank_mask:0xf bound_ctrl:1
	v_pk_fma_f32 v[128:129], v[38:39], v[58:59], v[128:129]
	v_pk_fma_f32 v[130:131], v[32:33], v[60:61], v[130:131]
	v_add_f32_dpp v166, v166, v166 row_half_mirror row_mask:0xf bank_mask:0xf bound_ctrl:1
	v_add_f32_dpp v168, v168, v168 row_half_mirror row_mask:0xf bank_mask:0xf bound_ctrl:1
	v_pk_fma_f32 v[132:133], v[34:35], v[62:63], v[132:133]
	v_mov_b32_e32 v167, v94
	v_pk_fma_f32 v[36:37], v[64:65], v[166:167], v[126:127] op_sel_hi:[1,0,1]
	v_pk_fma_f32 v[38:39], v[66:67], v[166:167], v[128:129] op_sel_hi:[1,0,1]
	v_pk_fma_f32 v[32:33], v[68:69], v[166:167], v[130:131] op_sel_hi:[1,0,1]
	v_pk_fma_f32 v[34:35], v[70:71], v[166:167], v[132:133] op_sel_hi:[1,0,1]
	v_pk_mul_f32 v[134:135], v[166:167], v[108:109]
	s_nop 0
	v_add_f32_e32 v136, v168, v134
	v_add_f32_e32 v136, v135, v136
	ds_write_b32 v95, v136 offset:768
	ds_read_b128 v[40:43], v120 offset:10240
	ds_read_b128 v[44:47], v120 offset:10256
	ds_read_b128 v[48:51], v120 offset:10496
	ds_read_b128 v[52:55], v120 offset:10512
	ds_read_b128 v[56:59], v120 offset:10752
	ds_read_b128 v[60:63], v120 offset:10768
	ds_read_b128 v[64:67], v120 offset:11008
	ds_read_b128 v[68:71], v120 offset:11024
	ds_read_b128 v[72:75], v120 offset:11264
	ds_read_b128 v[76:79], v120 offset:11280
	ds_read_b32 v94, v96 offset:22528
	ds_read_b64 v[108:109], v121 offset:24704
	s_waitcnt lgkmcnt(12)
	v_pk_mul_f32 v[122:123], v[38:39], v[192:193]
	v_pk_mul_f32 v[124:125], v[38:39], v[200:201]
	v_pk_fma_f32 v[122:123], v[36:37], v[190:191], v[122:123]
	v_pk_fma_f32 v[124:125], v[36:37], v[198:199], v[124:125]
	v_pk_fma_f32 v[122:123], v[32:33], v[194:195], v[122:123]
	v_pk_fma_f32 v[124:125], v[32:33], v[202:203], v[124:125]
	v_pk_fma_f32 v[122:123], v[34:35], v[196:197], v[122:123]
	v_pk_fma_f32 v[124:125], v[34:35], v[204:205], v[124:125]
	v_pk_mul_f32 v[126:127], v[222:223], v[230:231] op_sel_hi:[1,0]
	v_add_f32_e32 v166, v122, v123
	v_add_f32_e32 v168, v124, v125
	v_pk_mul_f32 v[128:129], v[224:225], v[230:231] op_sel_hi:[1,0]
	v_pk_mul_f32 v[130:131], v[226:227], v[230:231] op_sel_hi:[1,0]
	v_add_f32_dpp v166, v166, v166 quad_perm:[1,0,3,2] row_mask:0xf bank_mask:0xf bound_ctrl:1
	v_add_f32_dpp v168, v168, v168 quad_perm:[1,0,3,2] row_mask:0xf bank_mask:0xf bound_ctrl:1
	v_pk_mul_f32 v[132:133], v[228:229], v[230:231] op_sel_hi:[1,0]
	v_pk_fma_f32 v[126:127], v[36:37], v[206:207], v[126:127]
	v_add_f32_dpp v166, v166, v166 quad_perm:[2,3,0,1] row_mask:0xf bank_mask:0xf bound_ctrl:1
	v_add_f32_dpp v168, v168, v168 quad_perm:[2,3,0,1] row_mask:0xf bank_mask:0xf bound_ctrl:1
	v_pk_fma_f32 v[128:129], v[38:39], v[208:209], v[128:129]
	v_pk_fma_f32 v[130:131], v[32:33], v[210:211], v[130:131]
	v_add_f32_dpp v166, v166, v166 row_half_mirror row_mask:0xf bank_mask:0xf bound_ctrl:1
	v_add_f32_dpp v168, v168, v168 row_half_mirror row_mask:0xf bank_mask:0xf bound_ctrl:1
	v_pk_fma_f32 v[132:133], v[34:35], v[212:213], v[132:133]
	v_mov_b32_e32 v167, v230
	v_pk_fma_f32 v[36:37], v[214:215], v[166:167], v[126:127] op_sel_hi:[1,0,1]
	v_pk_fma_f32 v[38:39], v[216:217], v[166:167], v[128:129] op_sel_hi:[1,0,1]
	v_pk_fma_f32 v[32:33], v[218:219], v[166:167], v[130:131] op_sel_hi:[1,0,1]
	v_pk_fma_f32 v[34:35], v[220:221], v[166:167], v[132:133] op_sel_hi:[1,0,1]
	v_pk_mul_f32 v[134:135], v[166:167], v[232:233]
	s_nop 0
	v_add_f32_e32 v136, v168, v134
	v_add_f32_e32 v136, v135, v136
	ds_write_b32 v95, v136 offset:896
	ds_read_b128 v[190:193], v120 offset:11520
	ds_read_b128 v[194:197], v120 offset:11536
	ds_read_b128 v[198:201], v120 offset:11776
	ds_read_b128 v[202:205], v120 offset:11792
	ds_read_b128 v[206:209], v120 offset:12032
	ds_read_b128 v[210:213], v120 offset:12048
	ds_read_b128 v[214:217], v120 offset:12288
	ds_read_b128 v[218:221], v120 offset:12304
	ds_read_b128 v[222:225], v120 offset:12544
	ds_read_b128 v[226:229], v120 offset:12560
	ds_read_b32 v230, v96 offset:22784
	ds_read_b64 v[232:233], v121 offset:24720
	s_waitcnt lgkmcnt(12)
; #define SC_LOAD(t) { _Pragma("unroll") for (int q = 0; q < 5; ++q) { n[2 * q] = *(const LAS f32x4*)(opb + (t) * 320 + q * 64); n[2 * q + 1] = *(const LAS f32x4*)(opb + (t) * 320 + q * 64 + 4); } \
;                      nv = vvb[(t) * 64]; nbk = *(const LAS f32x2*)(scb + (t) * 4); }
; DI void scan_item(const __attribute__((address_space(4))) Args& a, LAS unsigned char* lds, int ws_, bool is_prompt, int seq, int h, int half, bool dry = false) {
;     ...
; #pragma unroll 4
;         for (int t = 0; t < SC_CH; ++t) {
;             f32x4 c[10];
; #pragma unroll
;             for (int q = 0; q < 10; ++q) c[q] = n[q];
;             const float v0 = nv; const f32x2 bk = nbk;
;             SC_LOAD(t + 1)
;             __builtin_amdgcn_sched_barrier(0);
;             f32x2 aA = sp[0] * c[0].xy, aY = sp[0] * c[2].xy;
;             aA = sp[1] * c[0].zw + aA; aY = sp[1] * c[2].zw + aY;
;             aA = sp[2] * c[1].xy + aA; aY = sp[2] * c[3].xy + aY;
;             aA = sp[3] * c[1].zw + aA; aY = sp[3] * c[3].zw + aY;
;             float da = aA.x + aA.y, dy = aY.x + aY.y;
;             asm("s_nop 1\n\t"
;                 "v_add_f32_dpp %0, %0, %0 quad_perm:[1,0,3,2] row_mask:0xf bank_mask:0xf bound_ctrl:1\n\t"
;                 "v_add_f32_dpp %1, %1, %1 quad_perm:[1,0,3,2] row_mask:0xf bank_mask:0xf bound_ctrl:1\n\t"
;                 "s_nop 0\n\t"
;                 "v_add_f32_dpp %0, %0, %0 quad_perm:[2,3,0,1] row_mask:0xf bank_mask:0xf bound_ctrl:1\n\t"
;                 "v_add_f32_dpp %1, %1, %1 quad_perm:[2,3,0,1] row_mask:0xf bank_mask:0xf bound_ctrl:1\n\t"
;                 "s_nop 0\n\t"
;                 "v_add_f32_dpp %0, %0, %0 row_half_mirror row_mask:0xf bank_mask:0xf bound_ctrl:1\n\t"
;                 "v_add_f32_dpp %1, %1, %1 row_half_mirror row_mask:0xf bank_mask:0xf bound_ctrl:1"
;                 : "+v"(da), "+v"(dy));
;             {
;                 f32x2 t0;
;                 t0 = c[8].xy * v0; t0 = c[6].xy * da + t0; sp[0] = sp[0] * c[4].xy + t0;
;                 t0 = c[8].zw * v0; t0 = c[6].zw * da + t0; sp[1] = sp[1] * c[4].zw + t0;
;                 t0 = c[9].xy * v0; t0 = c[7].xy * da + t0; sp[2] = sp[2] * c[5].xy + t0;
;                 t0 = c[9].zw * v0; t0 = c[7].zw * da + t0; sp[3] = sp[3] * c[5].zw + t0;
;             }
;             ybb[t * 32] = dy + da * bk.x + v0 * bk.y;
	v_pk_mul_f32 v[122:123], v[38:39], v[42:43]
	v_pk_mul_f32 v[124:125], v[38:39], v[50:51]
	v_pk_fma_f32 v[122:123], v[36:37], v[40:41], v[122:123]
	v_pk_fma_f32 v[124:125], v[36:37], v[48:49], v[124:125]
	v_pk_fma_f32 v[122:123], v[32:33], v[44:45], v[122:123]
	v_pk_fma_f32 v[124:125], v[32:33], v[52:53], v[124:125]
	v_pk_fma_f32 v[122:123], v[34:35], v[46:47], v[122:123]
	v_pk_fma_f32 v[124:125], v[34:35], v[54:55], v[124:125]
	v_pk_mul_f32 v[126:127], v[72:73], v[94:95] op_sel_hi:[1,0]
	v_add_f32_e32 v166, v122, v123
	v_add_f32_e32 v168, v124, v125
	v_pk_mul_f32 v[128:129], v[74:75], v[94:95] op_sel_hi:[1,0]
	v_pk_mul_f32 v[130:131], v[76:77], v[94:95] op_sel_hi:[1,0]
	v_add_f32_dpp v166, v166, v166 quad_perm:[1,0,3,2] row_mask:0xf bank_mask:0xf bound_ctrl:1
	v_add_f32_dpp v168, v168, v168 quad_perm:[1,0,3,2] row_mask:0xf bank_mask:0xf bound_ctrl:1
	v_pk_mul_f32 v[132:133], v[78:79], v[94:95] op_sel_hi:[1,0]
	v_pk_fma_f32 v[126:127], v[36:37], v[56:57], v[126:127]
	v_add_f32_dpp v166, v166, v166 quad_perm:[2,3,0,1] row_mask:0xf bank_mask:0xf bound_ctrl:1
	v_add_f32_dpp v168, v168, v168 quad_perm:[2,3,0,1] row_mask:0xf bank_mask:0xf bound_ctrl:1
	v_pk_fma_f32 v[128:129], v[38:39], v[58:59], v[128:129]
	v_pk_fma_f32 v[130:131], v[32:33], v[60:61], v[130:131]
	v_add_f32_dpp v166, v166, v166 row_half_mirror row_mask:0xf bank_mask:0xf bound_ctrl:1
	v_add_f32_dpp v168, v168, v168 row_half_mirror row_mask:0xf bank_mask:0xf bound_ctrl:1
	v_pk_fma_f32 v[132:133], v[34:35], v[62:63], v[132:133]
	v_mov_b32_e32 v167, v94
	v_pk_fma_f32 v[36:37], v[64:65], v[166:167], v[126:127] op_sel_hi:[1,0,1]
	v_pk_fma_f32 v[38:39], v[66:67], v[166:167], v[128:129] op_sel_hi:[1,0,1]
	v_pk_fma_f32 v[32:33], v[68:69], v[166:167], v[130:131] op_sel_hi:[1,0,1]
	v_pk_fma_f32 v[34:35], v[70:71], v[166:167], v[132:133] op_sel_hi:[1,0,1]
	v_pk_mul_f32 v[134:135], v[166:167], v[108:109]
	s_nop 0
	v_add_f32_e32 v136, v168, v134
	v_add_f32_e32 v136, v135, v136
	ds_write_b32 v95, v136 offset:1024
	ds_read_b128 v[40:43], v120 offset:12800
	ds_read_b128 v[44:47], v120 offset:12816
	ds_read_b128 v[48:51], v120 offset:13056
	ds_read_b128 v[52:55], v120 offset:13072
	ds_read_b128 v[56:59], v120 offset:13312
	ds_read_b128 v[60:63], v120 offset:13328
	ds_read_b128 v[64:67], v120 offset:13568
	ds_read_b128 v[68:71], v120 offset:13584
	ds_read_b128 v[72:75], v120 offset:13824
	ds_read_b128 v[76:79], v120 offset:13840
	ds_read_b32 v94, v96 offset:23040
	ds_read_b64 v[108:109], v121 offset:24736
	s_waitcnt lgkmcnt(12)
	v_pk_mul_f32 v[122:123], v[38:39], v[192:193]
	v_pk_mul_f32 v[124:125], v[38:39], v[200:201]
	v_pk_fma_f32 v[122:123], v[36:37], v[190:191], v[122:123]
	v_pk_fma_f32 v[124:125], v[36:37], v[198:199], v[124:125]
	v_pk_fma_f32 v[122:123], v[32:33], v[194:195], v[122:123]
	v_pk_fma_f32 v[124:125], v[32:33], v[202:203], v[124:125]
	v_pk_fma_f32 v[122:123], v[34:35], v[196:197], v[122:123]
	v_pk_fma_f32 v[124:125], v[34:35], v[204:205], v[124:125]
	v_pk_mul_f32 v[126:127], v[222:223], v[230:231] op_sel_hi:[1,0]
	v_add_f32_e32 v166, v122, v123
	v_add_f32_e32 v168, v124, v125
	v_pk_mul_f32 v[128:129], v[224:225], v[230:231] op_sel_hi:[1,0]
	v_pk_mul_f32 v[130:131], v[226:227], v[230:231] op_sel_hi:[1,0]
	v_add_f32_dpp v166, v166, v166 quad_perm:[1,0,3,2] row_mask:0xf bank_mask:0xf bound_ctrl:1
	v_add_f32_dpp v168, v168, v168 quad_perm:[1,0,3,2] row_mask:0xf bank_mask:0xf bound_ctrl:1
	v_pk_mul_f32 v[132:133], v[228:229], v[230:231] op_sel_hi:[1,0]
	v_pk_fma_f32 v[126:127], v[36:37], v[206:207], v[126:127]
	v_add_f32_dpp v166, v166, v166 quad_perm:[2,3,0,1] row_mask:0xf bank_mask:0xf bound_ctrl:1
	v_add_f32_dpp v168, v168, v168 quad_perm:[2,3,0,1] row_mask:0xf bank_mask:0xf bound_ctrl:1
	v_pk_fma_f32 v[128:129], v[38:39], v[208:209], v[128:129]
	v_pk_fma_f32 v[130:131], v[32:33], v[210:211], v[130:131]
	v_add_f32_dpp v166, v166, v166 row_half_mirror row_mask:0xf bank_mask:0xf bound_ctrl:1
	v_add_f32_dpp v168, v168, v168 row_half_mirror row_mask:0xf bank_mask:0xf bound_ctrl:1
	v_pk_fma_f32 v[132:133], v[34:35], v[212:213], v[132:133]
	v_mov_b32_e32 v167, v230
	v_pk_fma_f32 v[36:37], v[214:215], v[166:167], v[126:127] op_sel_hi:[1,0,1]
	v_pk_fma_f32 v[38:39], v[216:217], v[166:167], v[128:129] op_sel_hi:[1,0,1]
	v_pk_fma_f32 v[32:33], v[218:219], v[166:167], v[130:131] op_sel_hi:[1,0,1]
	v_pk_fma_f32 v[34:35], v[220:221], v[166:167], v[132:133] op_sel_hi:[1,0,1]
	v_pk_mul_f32 v[134:135], v[166:167], v[232:233]
	s_nop 0
	v_add_f32_e32 v136, v168, v134
	v_add_f32_e32 v136, v135, v136
	ds_write_b32 v95, v136 offset:1152
	ds_read_b128 v[190:193], v120 offset:14080
	ds_read_b128 v[194:197], v120 offset:14096
	ds_read_b128 v[198:201], v120 offset:14336
	ds_read_b128 v[202:205], v120 offset:14352
	ds_read_b128 v[206:209], v120 offset:14592
	ds_read_b128 v[210:213], v120 offset:14608
	ds_read_b128 v[214:217], v120 offset:14848
	ds_read_b128 v[218:221], v120 offset:14864
	ds_read_b128 v[222:225], v120 offset:15104
	ds_read_b128 v[226:229], v120 offset:15120
	ds_read_b32 v230, v96 offset:23296
	ds_read_b64 v[232:233], v121 offset:24752
	s_waitcnt lgkmcnt(12)
; #define SC_LOAD(t) { _Pragma("unroll") for (int q = 0; q < 5; ++q) { n[2 * q] = *(const LAS f32x4*)(opb + (t) * 320 + q * 64); n[2 * q + 1] = *(const LAS f32x4*)(opb + (t) * 320 + q * 64 + 4); } \
;                      nv = vvb[(t) * 64]; nbk = *(const LAS f32x2*)(scb + (t) * 4); }
; DI void scan_item(const __attribute__((address_space(4))) Args& a, LAS unsigned char* lds, int ws_, bool is_prompt, int seq, int h, int half, bool dry = false) {
;     ...
; #pragma unroll 4
;         for (int t = 0; t < SC_CH; ++t) {
;             f32x4 c[10];
; #pragma unroll
;             for (int q = 0; q < 10; ++q) c[q] = n[q];
;             const float v0 = nv; const f32x2 bk = nbk;
;             SC_LOAD(t + 1)
;             __builtin_amdgcn_sched_barrier(0);
;             f32x2 aA = sp[0] * c[0].xy, aY = sp[0] * c[2].xy;
;             aA = sp[1] * c[0].zw + aA; aY = sp[1] * c[2].zw + aY;
;             aA = sp[2] * c[1].xy + aA; aY = sp[2] * c[3].xy + aY;
;             aA = sp[3] * c[1].zw + aA; aY = sp[3] * c[3].zw + aY;
;             float da = aA.x + aA.y, dy = aY.x + aY.y;
;             asm("s_nop 1\n\t"
;                 "v_add_f32_dpp %0, %0, %0 quad_perm:[1,0,3,2] row_mask:0xf bank_mask:0xf bound_ctrl:1\n\t"
;                 "v_add_f32_dpp %1, %1, %1 quad_perm:[1,0,3,2] row_mask:0xf bank_mask:0xf bound_ctrl:1\n\t"
;                 "s_nop 0\n\t"
;                 "v_add_f32_dpp %0, %0, %0 quad_perm:[2,3,0,1] row_mask:0xf bank_mask:0xf bound_ctrl:1\n\t"
;                 "v_add_f32_dpp %1, %1, %1 quad_perm:[2,3,0,1] row_mask:0xf bank_mask:0xf bound_ctrl:1\n\t"
;                 "s_nop 0\n\t"
;                 "v_add_f32_dpp %0, %0, %0 row_half_mirror row_mask:0xf bank_mask:0xf bound_ctrl:1\n\t"
;                 "v_add_f32_dpp %1, %1, %1 row_half_mirror row_mask:0xf bank_mask:0xf bound_ctrl:1"
;                 : "+v"(da), "+v"(dy));
;             {
;                 f32x2 t0;
;                 t0 = c[8].xy * v0; t0 = c[6].xy * da + t0; sp[0] = sp[0] * c[4].xy + t0;
;                 t0 = c[8].zw * v0; t0 = c[6].zw * da + t0; sp[1] = sp[1] * c[4].zw + t0;
;                 t0 = c[9].xy * v0; t0 = c[7].xy * da + t0; sp[2] = sp[2] * c[5].xy + t0;
;                 t0 = c[9].zw * v0; t0 = c[7].zw * da + t0; sp[3] = sp[3] * c[5].zw + t0;
;             }
;             ybb[t * 32] = dy + da * bk.x + v0 * bk.y;
	v_pk_mul_f32 v[122:123], v[38:39], v[42:43]
	v_pk_mul_f32 v[124:125], v[38:39], v[50:51]
	v_pk_fma_f32 v[122:123], v[36:37], v[40:41], v[122:123]
	v_pk_fma_f32 v[124:125], v[36:37], v[48:49], v[124:125]
	v_pk_fma_f32 v[122:123], v[32:33], v[44:45], v[122:123]
	v_pk_fma_f32 v[124:125], v[32:33], v[52:53], v[124:125]
	v_pk_fma_f32 v[122:123], v[34:35], v[46:47], v[122:123]
	v_pk_fma_f32 v[124:125], v[34:35], v[54:55], v[124:125]
	v_pk_mul_f32 v[126:127], v[72:73], v[94:95] op_sel_hi:[1,0]
	v_add_f32_e32 v166, v122, v123
	v_add_f32_e32 v168, v124, v125
	v_pk_mul_f32 v[128:129], v[74:75], v[94:95] op_sel_hi:[1,0]
	v_pk_mul_f32 v[130:131], v[76:77], v[94:95] op_sel_hi:[1,0]
	v_add_f32_dpp v166, v166, v166 quad_perm:[1,0,3,2] row_mask:0xf bank_mask:0xf bound_ctrl:1
	v_add_f32_dpp v168, v168, v168 quad_perm:[1,0,3,2] row_mask:0xf bank_mask:0xf bound_ctrl:1
	v_pk_mul_f32 v[132:133], v[78:79], v[94:95] op_sel_hi:[1,0]
	v_pk_fma_f32 v[126:127], v[36:37], v[56:57], v[126:127]
	v_add_f32_dpp v166, v166, v166 quad_perm:[2,3,0,1] row_mask:0xf bank_mask:0xf bound_ctrl:1
	v_add_f32_dpp v168, v168, v168 quad_perm:[2,3,0,1] row_mask:0xf bank_mask:0xf bound_ctrl:1
	v_pk_fma_f32 v[128:129], v[38:39], v[58:59], v[128:129]
	v_pk_fma_f32 v[130:131], v[32:33], v[60:61], v[130:131]
	v_add_f32_dpp v166, v166, v166 row_half_mirror row_mask:0xf bank_mask:0xf bound_ctrl:1
	v_add_f32_dpp v168, v168, v168 row_half_mirror row_mask:0xf bank_mask:0xf bound_ctrl:1
	v_pk_fma_f32 v[132:133], v[34:35], v[62:63], v[132:133]
	v_mov_b32_e32 v167, v94
	v_pk_fma_f32 v[36:37], v[64:65], v[166:167], v[126:127] op_sel_hi:[1,0,1]
	v_pk_fma_f32 v[38:39], v[66:67], v[166:167], v[128:129] op_sel_hi:[1,0,1]
	v_pk_fma_f32 v[32:33], v[68:69], v[166:167], v[130:131] op_sel_hi:[1,0,1]
	v_pk_fma_f32 v[34:35], v[70:71], v[166:167], v[132:133] op_sel_hi:[1,0,1]
	v_pk_mul_f32 v[134:135], v[166:167], v[108:109]
	s_nop 0
	v_add_f32_e32 v136, v168, v134
	v_add_f32_e32 v136, v135, v136
	ds_write_b32 v95, v136 offset:1280
	ds_read_b128 v[40:43], v120 offset:15360
	ds_read_b128 v[44:47], v120 offset:15376
	ds_read_b128 v[48:51], v120 offset:15616
	ds_read_b128 v[52:55], v120 offset:15632
	ds_read_b128 v[56:59], v120 offset:15872
	ds_read_b128 v[60:63], v120 offset:15888
	ds_read_b128 v[64:67], v120 offset:16128
	ds_read_b128 v[68:71], v120 offset:16144
	ds_read_b128 v[72:75], v120 offset:16384
	ds_read_b128 v[76:79], v120 offset:16400
	ds_read_b32 v94, v96 offset:23552
	ds_read_b64 v[108:109], v121 offset:24768
	s_waitcnt lgkmcnt(12)
	v_pk_mul_f32 v[122:123], v[38:39], v[192:193]
	v_pk_mul_f32 v[124:125], v[38:39], v[200:201]
	v_pk_fma_f32 v[122:123], v[36:37], v[190:191], v[122:123]
	v_pk_fma_f32 v[124:125], v[36:37], v[198:199], v[124:125]
	v_pk_fma_f32 v[122:123], v[32:33], v[194:195], v[122:123]
	v_pk_fma_f32 v[124:125], v[32:33], v[202:203], v[124:125]
	v_pk_fma_f32 v[122:123], v[34:35], v[196:197], v[122:123]
	v_pk_fma_f32 v[124:125], v[34:35], v[204:205], v[124:125]
	v_pk_mul_f32 v[126:127], v[222:223], v[230:231] op_sel_hi:[1,0]
	v_add_f32_e32 v166, v122, v123
	v_add_f32_e32 v168, v124, v125
	v_pk_mul_f32 v[128:129], v[224:225], v[230:231] op_sel_hi:[1,0]
	v_pk_mul_f32 v[130:131], v[226:227], v[230:231] op_sel_hi:[1,0]
	v_add_f32_dpp v166, v166, v166 quad_perm:[1,0,3,2] row_mask:0xf bank_mask:0xf bound_ctrl:1
	v_add_f32_dpp v168, v168, v168 quad_perm:[1,0,3,2] row_mask:0xf bank_mask:0xf bound_ctrl:1
	v_pk_mul_f32 v[132:133], v[228:229], v[230:231] op_sel_hi:[1,0]
	v_pk_fma_f32 v[126:127], v[36:37], v[206:207], v[126:127]
	v_add_f32_dpp v166, v166, v166 quad_perm:[2,3,0,1] row_mask:0xf bank_mask:0xf bound_ctrl:1
	v_add_f32_dpp v168, v168, v168 quad_perm:[2,3,0,1] row_mask:0xf bank_mask:0xf bound_ctrl:1
	v_pk_fma_f32 v[128:129], v[38:39], v[208:209], v[128:129]
	v_pk_fma_f32 v[130:131], v[32:33], v[210:211], v[130:131]
	v_add_f32_dpp v166, v166, v166 row_half_mirror row_mask:0xf bank_mask:0xf bound_ctrl:1
	v_add_f32_dpp v168, v168, v168 row_half_mirror row_mask:0xf bank_mask:0xf bound_ctrl:1
	v_pk_fma_f32 v[132:133], v[34:35], v[212:213], v[132:133]
	v_mov_b32_e32 v167, v230
	v_pk_fma_f32 v[36:37], v[214:215], v[166:167], v[126:127] op_sel_hi:[1,0,1]
	v_pk_fma_f32 v[38:39], v[216:217], v[166:167], v[128:129] op_sel_hi:[1,0,1]
	v_pk_fma_f32 v[32:33], v[218:219], v[166:167], v[130:131] op_sel_hi:[1,0,1]
	v_pk_fma_f32 v[34:35], v[220:221], v[166:167], v[132:133] op_sel_hi:[1,0,1]
	v_pk_mul_f32 v[134:135], v[166:167], v[232:233]
	s_nop 0
	v_add_f32_e32 v136, v168, v134
	v_add_f32_e32 v136, v135, v136
	ds_write_b32 v95, v136 offset:1408
	ds_read_b128 v[190:193], v120 offset:16640
	ds_read_b128 v[194:197], v120 offset:16656
	ds_read_b128 v[198:201], v120 offset:16896
	ds_read_b128 v[202:205], v120 offset:16912
	ds_read_b128 v[206:209], v120 offset:17152
	ds_read_b128 v[210:213], v120 offset:17168
	ds_read_b128 v[214:217], v120 offset:17408
	ds_read_b128 v[218:221], v120 offset:17424
	ds_read_b128 v[222:225], v120 offset:17664
	ds_read_b128 v[226:229], v120 offset:17680
	ds_read_b32 v230, v96 offset:23808
	ds_read_b64 v[232:233], v121 offset:24784
	s_waitcnt lgkmcnt(12)
; #define SC_LOAD(t) { _Pragma("unroll") for (int q = 0; q < 5; ++q) { n[2 * q] = *(const LAS f32x4*)(opb + (t) * 320 + q * 64); n[2 * q + 1] = *(const LAS f32x4*)(opb + (t) * 320 + q * 64 + 4); } \
;                      nv = vvb[(t) * 64]; nbk = *(const LAS f32x2*)(scb + (t) * 4); }
; DI void scan_item(const __attribute__((address_space(4))) Args& a, LAS unsigned char* lds, int ws_, bool is_prompt, int seq, int h, int half, bool dry = false) {
;     ...
; #pragma unroll 4
;         for (int t = 0; t < SC_CH; ++t) {
;             f32x4 c[10];
; #pragma unroll
;             for (int q = 0; q < 10; ++q) c[q] = n[q];
;             const float v0 = nv; const f32x2 bk = nbk;
;             SC_LOAD(t + 1)
;             __builtin_amdgcn_sched_barrier(0);
;             f32x2 aA = sp[0] * c[0].xy, aY = sp[0] * c[2].xy;
;             aA = sp[1] * c[0].zw + aA; aY = sp[1] * c[2].zw + aY;
;             aA = sp[2] * c[1].xy + aA; aY = sp[2] * c[3].xy + aY;
;             aA = sp[3] * c[1].zw + aA; aY = sp[3] * c[3].zw + aY;
;             float da = aA.x + aA.y, dy = aY.x + aY.y;
;             asm("s_nop 1\n\t"
;                 "v_add_f32_dpp %0, %0, %0 quad_perm:[1,0,3,2] row_mask:0xf bank_mask:0xf bound_ctrl:1\n\t"
;                 "v_add_f32_dpp %1, %1, %1 quad_perm:[1,0,3,2] row_mask:0xf bank_mask:0xf bound_ctrl:1\n\t"
;                 "s_nop 0\n\t"
;                 "v_add_f32_dpp %0, %0, %0 quad_perm:[2,3,0,1] row_mask:0xf bank_mask:0xf bound_ctrl:1\n\t"
;                 "v_add_f32_dpp %1, %1, %1 quad_perm:[2,3,0,1] row_mask:0xf bank_mask:0xf bound_ctrl:1\n\t"
;                 "s_nop 0\n\t"
;                 "v_add_f32_dpp %0, %0, %0 row_half_mirror row_mask:0xf bank_mask:0xf bound_ctrl:1\n\t"
;                 "v_add_f32_dpp %1, %1, %1 row_half_mirror row_mask:0xf bank_mask:0xf bound_ctrl:1"
;                 : "+v"(da), "+v"(dy));
;             {
;                 f32x2 t0;
;                 t0 = c[8].xy * v0; t0 = c[6].xy * da + t0; sp[0] = sp[0] * c[4].xy + t0;
;                 t0 = c[8].zw * v0; t0 = c[6].zw * da + t0; sp[1] = sp[1] * c[4].zw + t0;
;                 t0 = c[9].xy * v0; t0 = c[7].xy * da + t0; sp[2] = sp[2] * c[5].xy + t0;
;                 t0 = c[9].zw * v0; t0 = c[7].zw * da + t0; sp[3] = sp[3] * c[5].zw + t0;
;             }
;             ybb[t * 32] = dy + da * bk.x + v0 * bk.y;
	v_pk_mul_f32 v[122:123], v[38:39], v[42:43]
	v_pk_mul_f32 v[124:125], v[38:39], v[50:51]
	v_pk_fma_f32 v[122:123], v[36:37], v[40:41], v[122:123]
	v_pk_fma_f32 v[124:125], v[36:37], v[48:49], v[124:125]
	v_pk_fma_f32 v[122:123], v[32:33], v[44:45], v[122:123]
	v_pk_fma_f32 v[124:125], v[32:33], v[52:53], v[124:125]
	v_pk_fma_f32 v[122:123], v[34:35], v[46:47], v[122:123]
	v_pk_fma_f32 v[124:125], v[34:35], v[54:55], v[124:125]
	v_pk_mul_f32 v[126:127], v[72:73], v[94:95] op_sel_hi:[1,0]
	v_add_f32_e32 v166, v122, v123
	v_add_f32_e32 v168, v124, v125
	v_pk_mul_f32 v[128:129], v[74:75], v[94:95] op_sel_hi:[1,0]
	v_pk_mul_f32 v[130:131], v[76:77], v[94:95] op_sel_hi:[1,0]
	v_add_f32_dpp v166, v166, v166 quad_perm:[1,0,3,2] row_mask:0xf bank_mask:0xf bound_ctrl:1
	v_add_f32_dpp v168, v168, v168 quad_perm:[1,0,3,2] row_mask:0xf bank_mask:0xf bound_ctrl:1
	v_pk_mul_f32 v[132:133], v[78:79], v[94:95] op_sel_hi:[1,0]
	v_pk_fma_f32 v[126:127], v[36:37], v[56:57], v[126:127]
	v_add_f32_dpp v166, v166, v166 quad_perm:[2,3,0,1] row_mask:0xf bank_mask:0xf bound_ctrl:1
	v_add_f32_dpp v168, v168, v168 quad_perm:[2,3,0,1] row_mask:0xf bank_mask:0xf bound_ctrl:1
	v_pk_fma_f32 v[128:129], v[38:39], v[58:59], v[128:129]
	v_pk_fma_f32 v[130:131], v[32:33], v[60:61], v[130:131]
	v_add_f32_dpp v166, v166, v166 row_half_mirror row_mask:0xf bank_mask:0xf bound_ctrl:1
	v_add_f32_dpp v168, v168, v168 row_half_mirror row_mask:0xf bank_mask:0xf bound_ctrl:1
	v_pk_fma_f32 v[132:133], v[34:35], v[62:63], v[132:133]
	v_mov_b32_e32 v167, v94
	v_pk_fma_f32 v[36:37], v[64:65], v[166:167], v[126:127] op_sel_hi:[1,0,1]
	v_pk_fma_f32 v[38:39], v[66:67], v[166:167], v[128:129] op_sel_hi:[1,0,1]
	v_pk_fma_f32 v[32:33], v[68:69], v[166:167], v[130:131] op_sel_hi:[1,0,1]
	v_pk_fma_f32 v[34:35], v[70:71], v[166:167], v[132:133] op_sel_hi:[1,0,1]
	v_pk_mul_f32 v[134:135], v[166:167], v[108:109]
	s_nop 0
	v_add_f32_e32 v136, v168, v134
	v_add_f32_e32 v136, v135, v136
	ds_write_b32 v95, v136 offset:1536
	ds_read_b128 v[40:43], v120 offset:17920
	ds_read_b128 v[44:47], v120 offset:17936
	ds_read_b128 v[48:51], v120 offset:18176
	ds_read_b128 v[52:55], v120 offset:18192
	ds_read_b128 v[56:59], v120 offset:18432
	ds_read_b128 v[60:63], v120 offset:18448
	ds_read_b128 v[64:67], v120 offset:18688
	ds_read_b128 v[68:71], v120 offset:18704
	ds_read_b128 v[72:75], v120 offset:18944
	ds_read_b128 v[76:79], v120 offset:18960
	ds_read_b32 v94, v96 offset:24064
	ds_read_b64 v[108:109], v121 offset:24800
	s_waitcnt lgkmcnt(12)
	v_pk_mul_f32 v[122:123], v[38:39], v[192:193]
	v_pk_mul_f32 v[124:125], v[38:39], v[200:201]
	v_pk_fma_f32 v[122:123], v[36:37], v[190:191], v[122:123]
	v_pk_fma_f32 v[124:125], v[36:37], v[198:199], v[124:125]
	v_pk_fma_f32 v[122:123], v[32:33], v[194:195], v[122:123]
	v_pk_fma_f32 v[124:125], v[32:33], v[202:203], v[124:125]
	v_pk_fma_f32 v[122:123], v[34:35], v[196:197], v[122:123]
	v_pk_fma_f32 v[124:125], v[34:35], v[204:205], v[124:125]
	v_pk_mul_f32 v[126:127], v[222:223], v[230:231] op_sel_hi:[1,0]
	v_add_f32_e32 v166, v122, v123
	v_add_f32_e32 v168, v124, v125
	v_pk_mul_f32 v[128:129], v[224:225], v[230:231] op_sel_hi:[1,0]
	v_pk_mul_f32 v[130:131], v[226:227], v[230:231] op_sel_hi:[1,0]
	v_add_f32_dpp v166, v166, v166 quad_perm:[1,0,3,2] row_mask:0xf bank_mask:0xf bound_ctrl:1
	v_add_f32_dpp v168, v168, v168 quad_perm:[1,0,3,2] row_mask:0xf bank_mask:0xf bound_ctrl:1
	v_pk_mul_f32 v[132:133], v[228:229], v[230:231] op_sel_hi:[1,0]
	v_pk_fma_f32 v[126:127], v[36:37], v[206:207], v[126:127]
	v_add_f32_dpp v166, v166, v166 quad_perm:[2,3,0,1] row_mask:0xf bank_mask:0xf bound_ctrl:1
	v_add_f32_dpp v168, v168, v168 quad_perm:[2,3,0,1] row_mask:0xf bank_mask:0xf bound_ctrl:1
	v_pk_fma_f32 v[128:129], v[38:39], v[208:209], v[128:129]
	v_pk_fma_f32 v[130:131], v[32:33], v[210:211], v[130:131]
	v_add_f32_dpp v166, v166, v166 row_half_mirror row_mask:0xf bank_mask:0xf bound_ctrl:1
	v_add_f32_dpp v168, v168, v168 row_half_mirror row_mask:0xf bank_mask:0xf bound_ctrl:1
	v_pk_fma_f32 v[132:133], v[34:35], v[212:213], v[132:133]
	v_mov_b32_e32 v167, v230
	v_pk_fma_f32 v[36:37], v[214:215], v[166:167], v[126:127] op_sel_hi:[1,0,1]
	v_pk_fma_f32 v[38:39], v[216:217], v[166:167], v[128:129] op_sel_hi:[1,0,1]
	v_pk_fma_f32 v[32:33], v[218:219], v[166:167], v[130:131] op_sel_hi:[1,0,1]
	v_pk_fma_f32 v[34:35], v[220:221], v[166:167], v[132:133] op_sel_hi:[1,0,1]
	v_pk_mul_f32 v[134:135], v[166:167], v[232:233]
	s_nop 0
	v_add_f32_e32 v136, v168, v134
	v_add_f32_e32 v136, v135, v136
	ds_write_b32 v95, v136 offset:1664
	ds_read_b128 v[190:193], v120 offset:19200
	ds_read_b128 v[194:197], v120 offset:19216
	ds_read_b128 v[198:201], v120 offset:19456
	ds_read_b128 v[202:205], v120 offset:19472
	ds_read_b128 v[206:209], v120 offset:19712
	ds_read_b128 v[210:213], v120 offset:19728
	ds_read_b128 v[214:217], v120 offset:19968
	ds_read_b128 v[218:221], v120 offset:19984
	ds_read_b128 v[222:225], v120 offset:20224
	ds_read_b128 v[226:229], v120 offset:20240
	ds_read_b32 v230, v96 offset:24320
	ds_read_b64 v[232:233], v121 offset:24816
	s_waitcnt lgkmcnt(12)
; DI void scan_item(const __attribute__((address_space(4))) Args& a, LAS unsigned char* lds, int ws_, bool is_prompt, int seq, int h, int half, bool dry = false) {
;     ...
; #pragma unroll 4
;         for (int t = 0; t < SC_CH; ++t) {
;             f32x4 c[10];
; #pragma unroll
;             for (int q = 0; q < 10; ++q) c[q] = n[q];
;             const float v0 = nv; const f32x2 bk = nbk;
;             SC_LOAD(t + 1)
;             __builtin_amdgcn_sched_barrier(0);
;             f32x2 aA = sp[0] * c[0].xy, aY = sp[0] * c[2].xy;
;             aA = sp[1] * c[0].zw + aA; aY = sp[1] * c[2].zw + aY;
;             aA = sp[2] * c[1].xy + aA; aY = sp[2] * c[3].xy + aY;
;             aA = sp[3] * c[1].zw + aA; aY = sp[3] * c[3].zw + aY;
;             float da = aA.x + aA.y, dy = aY.x + aY.y;
;             asm("s_nop 1\n\t"
;                 "v_add_f32_dpp %0, %0, %0 quad_perm:[1,0,3,2] row_mask:0xf bank_mask:0xf bound_ctrl:1\n\t"
;                 "v_add_f32_dpp %1, %1, %1 quad_perm:[1,0,3,2] row_mask:0xf bank_mask:0xf bound_ctrl:1\n\t"
;                 "s_nop 0\n\t"
;                 "v_add_f32_dpp %0, %0, %0 quad_perm:[2,3,0,1] row_mask:0xf bank_mask:0xf bound_ctrl:1\n\t"
;                 "v_add_f32_dpp %1, %1, %1 quad_perm:[2,3,0,1] row_mask:0xf bank_mask:0xf bound_ctrl:1\n\t"
;                 "s_nop 0\n\t"
;                 "v_add_f32_dpp %0, %0, %0 row_half_mirror row_mask:0xf bank_mask:0xf bound_ctrl:1\n\t"
;                 "v_add_f32_dpp %1, %1, %1 row_half_mirror row_mask:0xf bank_mask:0xf bound_ctrl:1"
;                 : "+v"(da), "+v"(dy));
;             {
;                 f32x2 t0;
;                 t0 = c[8].xy * v0; t0 = c[6].xy * da + t0; sp[0] = sp[0] * c[4].xy + t0;
;                 t0 = c[8].zw * v0; t0 = c[6].zw * da + t0; sp[1] = sp[1] * c[4].zw + t0;
;                 t0 = c[9].xy * v0; t0 = c[7].xy * da + t0; sp[2] = sp[2] * c[5].xy + t0;
;                 t0 = c[9].zw * v0; t0 = c[7].zw * da + t0; sp[3] = sp[3] * c[5].zw + t0;
;             }
;             ybb[t * 32] = dy + da * bk.x + v0 * bk.y;
;         }
;     ...
;     };
;     if (!consumer) { load_raw(0); produce(0, 0); if (NCH > 1) load_raw(1); }
;     __syncthreads();
;     for (int ch = 0; ch < NCH; ++ch) {
;         if (consumer) consume(ch & 1);
	v_pk_mul_f32 v[122:123], v[38:39], v[42:43]
	v_pk_mul_f32 v[124:125], v[38:39], v[50:51]
	v_pk_fma_f32 v[122:123], v[36:37], v[40:41], v[122:123]
	v_pk_fma_f32 v[124:125], v[36:37], v[48:49], v[124:125]
	v_pk_fma_f32 v[122:123], v[32:33], v[44:45], v[122:123]
	v_pk_fma_f32 v[124:125], v[32:33], v[52:53], v[124:125]
	v_pk_fma_f32 v[122:123], v[34:35], v[46:47], v[122:123]
	v_pk_fma_f32 v[124:125], v[34:35], v[54:55], v[124:125]
	v_pk_mul_f32 v[126:127], v[72:73], v[94:95] op_sel_hi:[1,0]
	v_add_f32_e32 v166, v122, v123
	v_add_f32_e32 v168, v124, v125
	v_pk_mul_f32 v[128:129], v[74:75], v[94:95] op_sel_hi:[1,0]
	v_pk_mul_f32 v[130:131], v[76:77], v[94:95] op_sel_hi:[1,0]
	v_add_f32_dpp v166, v166, v166 quad_perm:[1,0,3,2] row_mask:0xf bank_mask:0xf bound_ctrl:1
	v_add_f32_dpp v168, v168, v168 quad_perm:[1,0,3,2] row_mask:0xf bank_mask:0xf bound_ctrl:1
	v_pk_mul_f32 v[132:133], v[78:79], v[94:95] op_sel_hi:[1,0]
	v_pk_fma_f32 v[126:127], v[36:37], v[56:57], v[126:127]
	v_add_f32_dpp v166, v166, v166 quad_perm:[2,3,0,1] row_mask:0xf bank_mask:0xf bound_ctrl:1
	v_add_f32_dpp v168, v168, v168 quad_perm:[2,3,0,1] row_mask:0xf bank_mask:0xf bound_ctrl:1
	v_pk_fma_f32 v[128:129], v[38:39], v[58:59], v[128:129]
	v_pk_fma_f32 v[130:131], v[32:33], v[60:61], v[130:131]
	v_add_f32_dpp v166, v166, v166 row_half_mirror row_mask:0xf bank_mask:0xf bound_ctrl:1
	v_add_f32_dpp v168, v168, v168 row_half_mirror row_mask:0xf bank_mask:0xf bound_ctrl:1
	v_pk_fma_f32 v[132:133], v[34:35], v[62:63], v[132:133]
	v_mov_b32_e32 v167, v94
	v_pk_fma_f32 v[36:37], v[64:65], v[166:167], v[126:127] op_sel_hi:[1,0,1]
	v_pk_fma_f32 v[38:39], v[66:67], v[166:167], v[128:129] op_sel_hi:[1,0,1]
	v_pk_fma_f32 v[32:33], v[68:69], v[166:167], v[130:131] op_sel_hi:[1,0,1]
	v_pk_fma_f32 v[34:35], v[70:71], v[166:167], v[132:133] op_sel_hi:[1,0,1]
	v_pk_mul_f32 v[134:135], v[166:167], v[108:109]
	s_nop 0
	v_add_f32_e32 v136, v168, v134
	v_add_f32_e32 v136, v135, v136
	ds_write_b32 v95, v136 offset:1792
	s_waitcnt lgkmcnt(0)
	v_pk_mul_f32 v[122:123], v[38:39], v[192:193]
	v_pk_mul_f32 v[124:125], v[38:39], v[200:201]
	v_pk_fma_f32 v[122:123], v[36:37], v[190:191], v[122:123]
	v_pk_fma_f32 v[124:125], v[36:37], v[198:199], v[124:125]
	v_pk_fma_f32 v[122:123], v[32:33], v[194:195], v[122:123]
	v_pk_fma_f32 v[124:125], v[32:33], v[202:203], v[124:125]
	v_pk_fma_f32 v[122:123], v[34:35], v[196:197], v[122:123]
	v_pk_fma_f32 v[124:125], v[34:35], v[204:205], v[124:125]
	v_pk_mul_f32 v[126:127], v[222:223], v[230:231] op_sel_hi:[1,0]
	v_add_f32_e32 v166, v122, v123
	v_add_f32_e32 v168, v124, v125
	v_pk_mul_f32 v[128:129], v[224:225], v[230:231] op_sel_hi:[1,0]
	v_pk_mul_f32 v[130:131], v[226:227], v[230:231] op_sel_hi:[1,0]
	v_add_f32_dpp v166, v166, v166 quad_perm:[1,0,3,2] row_mask:0xf bank_mask:0xf bound_ctrl:1
	v_add_f32_dpp v168, v168, v168 quad_perm:[1,0,3,2] row_mask:0xf bank_mask:0xf bound_ctrl:1
	v_pk_mul_f32 v[132:133], v[228:229], v[230:231] op_sel_hi:[1,0]
	v_pk_fma_f32 v[126:127], v[36:37], v[206:207], v[126:127]
	v_add_f32_dpp v166, v166, v166 quad_perm:[2,3,0,1] row_mask:0xf bank_mask:0xf bound_ctrl:1
	v_add_f32_dpp v168, v168, v168 quad_perm:[2,3,0,1] row_mask:0xf bank_mask:0xf bound_ctrl:1
	v_pk_fma_f32 v[128:129], v[38:39], v[208:209], v[128:129]
	v_pk_fma_f32 v[130:131], v[32:33], v[210:211], v[130:131]
	v_add_f32_dpp v166, v166, v166 row_half_mirror row_mask:0xf bank_mask:0xf bound_ctrl:1
	v_add_f32_dpp v168, v168, v168 row_half_mirror row_mask:0xf bank_mask:0xf bound_ctrl:1
	v_pk_fma_f32 v[132:133], v[34:35], v[212:213], v[132:133]
	v_mov_b32_e32 v167, v230
	v_pk_fma_f32 v[36:37], v[214:215], v[166:167], v[126:127] op_sel_hi:[1,0,1]
	v_pk_fma_f32 v[38:39], v[216:217], v[166:167], v[128:129] op_sel_hi:[1,0,1]
	v_pk_fma_f32 v[32:33], v[218:219], v[166:167], v[130:131] op_sel_hi:[1,0,1]
	v_pk_fma_f32 v[34:35], v[220:221], v[166:167], v[132:133] op_sel_hi:[1,0,1]
	v_pk_mul_f32 v[134:135], v[166:167], v[232:233]
	s_nop 0
	v_add_f32_e32 v136, v168, v134
	v_add_f32_e32 v136, v135, v136
	ds_write_b32 v95, v136 offset:1920
	s_add_i32 s24, s24, 1
	s_branch .LBB0_1524
